# attention: row-sum accumulation moved ahead of the K/V staging wait (off the post-wait critical section)
# speedup vs baseline: 1.0148x; 1.0009x over previous
.LBB0_375:
	s_or_b64 exec, exec, s[14:15]
	s_add_i32 s14, s17, 1
	s_ashr_i32 s3, s2, 31
	s_bitcmp1_b32 s17, 0
	v_lshl_add_u64 v[2:3], s[2:3], 1, v[130:131]
	s_cselect_b32 s2, 0x2e00, 0
	s_add_i32 s2, s18, s2
	v_add3_u32 v0, s2, v153, v154
	global_load_dwordx4 v[94:97], v[2:3], off
	ds_read_b128 v[132:135], v0
	ds_read_b128 v[136:139], v0 offset:32
	ds_read_b128 v[140:143], v0 offset:64
	ds_read_b128 v[160:163], v0 offset:96
	ds_read_b128 v[164:167], v0 offset:128
	ds_read_b128 v[168:171], v0 offset:160
	v_add3_u32 v0, s2, v102, v155
	v_add_u32_e32 v2, 0x1800, v0
	v_add_u32_e32 v0, 0x2000, v0
	ds_read2_b64 v[172:175], v2 offset0:64 offset1:66
	ds_read2_b64 v[176:179], v2 offset0:68 offset1:70
	ds_read2_b64 v[180:183], v0 offset0:128 offset1:130
	ds_read2_b64 v[184:187], v0 offset0:132 offset1:134
	s_bitcmp1_b32 s14, 0
	s_cselect_b32 s2, 0x2e00, 0
	s_waitcnt lgkmcnt(9)
	v_mfma_f32_32x32x16_bf16 v[48:63], v[132:135], v[70:73], 0
	s_add_i32 s15, s18, s2
	s_waitcnt lgkmcnt(8)
	v_mfma_f32_32x32x16_bf16 v[48:63], v[136:139], v[74:77], v[48:63]
	s_waitcnt lgkmcnt(7)
	v_mfma_f32_32x32x16_bf16 v[48:63], v[140:143], v[78:81], v[48:63]
	s_waitcnt lgkmcnt(6)
	v_mfma_f32_32x32x16_bf16 v[48:63], v[160:163], v[82:85], v[48:63]
	s_waitcnt lgkmcnt(5)
	v_mfma_f32_32x32x16_bf16 v[48:63], v[164:167], v[86:89], v[48:63]
	s_waitcnt lgkmcnt(4)
	v_mfma_f32_32x32x16_bf16 v[48:63], v[168:171], v[90:93], v[48:63]
	s_nop 11
	v_max_f32_e32 v0, v49, v49
	v_max_f32_e32 v2, v48, v48
	v_max_f32_e32 v0, v2, v0
	v_max3_f32 v0, v0, v50, v51
	v_max3_f32 v0, v0, v52, v53
	v_max3_f32 v0, v0, v54, v55
	v_max3_f32 v0, v0, v56, v57
	v_max3_f32 v0, v0, v58, v59
	v_max3_f32 v0, v0, v60, v61
	v_max3_f32 v0, v0, v62, v63
	ds_bpermute_b32 v2, v103, v0
	s_waitcnt lgkmcnt(0)
	v_max3_f32 v115, v117, v0, v2
	v_sub_f32_e32 v0, v117, v115
	v_sub_f32_e32 v2, v48, v115
	v_sub_f32_e32 v3, v49, v115
	v_sub_f32_e32 v4, v50, v115
	v_sub_f32_e32 v5, v51, v115
	v_sub_f32_e32 v6, v52, v115
	v_sub_f32_e32 v7, v53, v115
	v_sub_f32_e32 v8, v54, v115
	v_sub_f32_e32 v9, v55, v115
	v_exp_f32_e32 v2, v2
	v_exp_f32_e32 v3, v3
	v_exp_f32_e32 v4, v4
	v_exp_f32_e32 v5, v5
	v_exp_f32_e32 v6, v6
	v_exp_f32_e32 v7, v7
	v_exp_f32_e32 v8, v8
	v_exp_f32_e32 v9, v9
	v_exp_f32_e32 v0, v0
	v_cvt_pk_bf16_f32 v48, v2, v3
	v_cvt_pk_bf16_f32 v49, v4, v5
	v_cvt_pk_bf16_f32 v50, v6, v7
	v_pk_mul_f32 v[46:47], v[46:47], v[0:1] op_sel_hi:[1,0]
	v_pk_mul_f32 v[44:45], v[44:45], v[0:1] op_sel_hi:[1,0]
	v_pk_mul_f32 v[42:43], v[42:43], v[0:1] op_sel_hi:[1,0]
	v_pk_mul_f32 v[40:41], v[40:41], v[0:1] op_sel_hi:[1,0]
	v_pk_mul_f32 v[38:39], v[38:39], v[0:1] op_sel_hi:[1,0]
	v_pk_mul_f32 v[36:37], v[36:37], v[0:1] op_sel_hi:[1,0]
	v_pk_mul_f32 v[34:35], v[34:35], v[0:1] op_sel_hi:[1,0]
	v_pk_mul_f32 v[32:33], v[32:33], v[0:1] op_sel_hi:[1,0]
	v_pk_mul_f32 v[30:31], v[30:31], v[0:1] op_sel_hi:[1,0]
	v_cvt_pk_bf16_f32 v51, v8, v9
	v_pk_mul_f32 v[28:29], v[28:29], v[0:1] op_sel_hi:[1,0]
	v_pk_mul_f32 v[26:27], v[26:27], v[0:1] op_sel_hi:[1,0]
	v_pk_mul_f32 v[24:25], v[24:25], v[0:1] op_sel_hi:[1,0]
	v_pk_mul_f32 v[22:23], v[22:23], v[0:1] op_sel_hi:[1,0]
	v_pk_mul_f32 v[20:21], v[20:21], v[0:1] op_sel_hi:[1,0]
	v_pk_mul_f32 v[18:19], v[18:19], v[0:1] op_sel_hi:[1,0]
	v_pk_mul_f32 v[16:17], v[16:17], v[0:1] op_sel_hi:[1,0]
	v_mfma_f32_32x32x16_bf16 v[32:47], v[172:175], v[48:51], v[32:47]
	v_sub_f32_e32 v10, v56, v115
	v_sub_f32_e32 v11, v57, v115
	v_sub_f32_e32 v12, v58, v115
	v_sub_f32_e32 v13, v59, v115
	v_sub_f32_e32 v14, v60, v115
	v_sub_f32_e32 v15, v61, v115
	v_sub_f32_e32 v52, v62, v115
	v_mfma_f32_32x32x16_bf16 v[16:31], v[180:183], v[48:51], v[16:31]
	v_sub_f32_e32 v49, v63, v115
	v_exp_f32_e32 v10, v10
	v_exp_f32_e32 v11, v11
	v_exp_f32_e32 v12, v12
	v_exp_f32_e32 v13, v13
	v_exp_f32_e32 v14, v14
	v_exp_f32_e32 v15, v15
	v_exp_f32_e32 v48, v52
	v_exp_f32_e32 v49, v49
	v_cvt_pk_bf16_f32 v50, v10, v11
	v_cvt_pk_bf16_f32 v51, v12, v13
	v_cvt_pk_bf16_f32 v52, v14, v15
	v_cvt_pk_bf16_f32 v53, v48, v49
	s_nop 1
	v_mfma_f32_32x32x16_bf16 v[32:47], v[176:179], v[50:53], v[32:47]
	v_mfma_f32_32x32x16_bf16 v[16:31], v[184:187], v[50:53], v[16:31]
	v_add_f32_e32 v2, 0, v2
	v_add_f32_e32 v2, v3, v2
	v_add_f32_e32 v2, v4, v2
	v_add_f32_e32 v2, v5, v2
	v_add_f32_e32 v2, v6, v2
	v_add_f32_e32 v2, v7, v2
	v_add_f32_e32 v2, v8, v2
	v_add_f32_e32 v2, v9, v2
	v_add_f32_e32 v2, v10, v2
	v_add_f32_e32 v2, v11, v2
	v_add_f32_e32 v2, v12, v2
	v_add_f32_e32 v2, v13, v2
	v_add_f32_e32 v2, v14, v2
	v_add_f32_e32 v2, v15, v2
	v_add_f32_e32 v2, v48, v2
	v_add_f32_e32 v188, v49, v2
	v_fmac_f32_e32 v188, v113, v0
	v_add3_u32 v50, s15, v148, v149
	s_waitcnt vmcnt(1)
	ds_write_b128 v50, v[98:101]
	s_and_saveexec_b64 s[2:3], s[0:1]
	v_add3_u32 v50, s15, v150, v156
	ds_write_b128 v50, v[66:69]
	s_or_b64 exec, exec, s[2:3]
	s_add_i32 s16, s16, 32
	v_mov_b32_e32 v98, v188
	v_add3_u32 v0, s15, v151, v152
	s_cmp_eq_u32 s14, 39
	s_waitcnt vmcnt(0)
	ds_write_b128 v0, v[94:97] offset:6656
	s_waitcnt lgkmcnt(0)
	s_barrier
	s_cbranch_scc1 .LBB0_379
	v_mov_b32_e32 v113, v98
	v_mov_b32_e32 v117, v115
	s_mov_b32 s17, s14
	s_branch .LBB0_373

.LBB0_391:
	s_or_b64 exec, exec, s[2:3]
	s_bitcmp1_b32 s7, 0
	s_cselect_b32 s3, 0, 0x2e00
	s_cselect_b32 s2, 0x2e00, 0
	s_add_i32 s3, s18, s3
	v_add3_u32 v0, s3, v153, v154
	global_load_dwordx4 v[92:95], v[126:127], off
	ds_read_b128 v[128:131], v0
	ds_read_b128 v[132:135], v0 offset:32
	ds_read_b128 v[136:139], v0 offset:64
	ds_read_b128 v[160:163], v0 offset:96
	ds_read_b128 v[164:167], v0 offset:128
	ds_read_b128 v[168:171], v0 offset:160
	v_add3_u32 v0, s3, v102, v155
	v_add_u32_e32 v2, 0x1800, v0
	v_add_u32_e32 v0, 0x2000, v0
	ds_read2_b64 v[172:175], v2 offset0:64 offset1:66
	ds_read2_b64 v[176:179], v2 offset0:68 offset1:70
	ds_read2_b64 v[180:183], v0 offset0:128 offset1:130
	ds_read2_b64 v[184:187], v0 offset0:132 offset1:134
	s_add_i32 s8, s18, s2
	s_waitcnt lgkmcnt(9)
	v_mfma_f32_32x32x16_bf16 v[48:63], v[128:131], v[68:71], 0
	s_waitcnt lgkmcnt(8)
	v_mfma_f32_32x32x16_bf16 v[48:63], v[132:135], v[72:75], v[48:63]
	s_waitcnt lgkmcnt(7)
	v_mfma_f32_32x32x16_bf16 v[48:63], v[136:139], v[76:79], v[48:63]
	s_waitcnt lgkmcnt(6)
	v_mfma_f32_32x32x16_bf16 v[48:63], v[160:163], v[80:83], v[48:63]
	s_waitcnt lgkmcnt(5)
	v_mfma_f32_32x32x16_bf16 v[48:63], v[164:167], v[84:87], v[48:63]
	s_waitcnt lgkmcnt(4)
	v_mfma_f32_32x32x16_bf16 v[48:63], v[168:171], v[88:91], v[48:63]
	s_nop 11
	v_max_f32_e32 v0, v49, v49
	v_max_f32_e32 v2, v48, v48
	v_max_f32_e32 v0, v2, v0
	v_max3_f32 v0, v0, v50, v51
	v_max3_f32 v0, v0, v52, v53
	v_max3_f32 v0, v0, v54, v55
	v_max3_f32 v0, v0, v56, v57
	v_max3_f32 v0, v0, v58, v59
	v_max3_f32 v0, v0, v60, v61
	v_max3_f32 v0, v0, v62, v63
	ds_bpermute_b32 v2, v103, v0
	s_waitcnt lgkmcnt(0)
	v_max3_f32 v119, v121, v0, v2
	v_sub_f32_e32 v0, v121, v119
	v_sub_f32_e32 v2, v48, v119
	v_sub_f32_e32 v3, v49, v119
	v_sub_f32_e32 v4, v50, v119
	v_sub_f32_e32 v5, v51, v119
	v_sub_f32_e32 v6, v52, v119
	v_sub_f32_e32 v7, v53, v119
	v_sub_f32_e32 v8, v54, v119
	v_sub_f32_e32 v9, v55, v119
	v_exp_f32_e32 v2, v2
	v_exp_f32_e32 v3, v3
	v_exp_f32_e32 v4, v4
	v_exp_f32_e32 v5, v5
	v_exp_f32_e32 v6, v6
	v_exp_f32_e32 v7, v7
	v_exp_f32_e32 v8, v8
	v_exp_f32_e32 v9, v9
	v_exp_f32_e32 v0, v0
	v_cvt_pk_bf16_f32 v48, v2, v3
	v_cvt_pk_bf16_f32 v49, v4, v5
	v_cvt_pk_bf16_f32 v50, v6, v7
	v_pk_mul_f32 v[46:47], v[46:47], v[0:1] op_sel_hi:[1,0]
	v_pk_mul_f32 v[44:45], v[44:45], v[0:1] op_sel_hi:[1,0]
	v_pk_mul_f32 v[42:43], v[42:43], v[0:1] op_sel_hi:[1,0]
	v_pk_mul_f32 v[40:41], v[40:41], v[0:1] op_sel_hi:[1,0]
	v_pk_mul_f32 v[38:39], v[38:39], v[0:1] op_sel_hi:[1,0]
	v_pk_mul_f32 v[36:37], v[36:37], v[0:1] op_sel_hi:[1,0]
	v_pk_mul_f32 v[34:35], v[34:35], v[0:1] op_sel_hi:[1,0]
	v_pk_mul_f32 v[32:33], v[32:33], v[0:1] op_sel_hi:[1,0]
	v_pk_mul_f32 v[30:31], v[30:31], v[0:1] op_sel_hi:[1,0]
	v_cvt_pk_bf16_f32 v51, v8, v9
	v_pk_mul_f32 v[28:29], v[28:29], v[0:1] op_sel_hi:[1,0]
	v_pk_mul_f32 v[26:27], v[26:27], v[0:1] op_sel_hi:[1,0]
	v_pk_mul_f32 v[24:25], v[24:25], v[0:1] op_sel_hi:[1,0]
	v_pk_mul_f32 v[22:23], v[22:23], v[0:1] op_sel_hi:[1,0]
	v_pk_mul_f32 v[20:21], v[20:21], v[0:1] op_sel_hi:[1,0]
	v_pk_mul_f32 v[18:19], v[18:19], v[0:1] op_sel_hi:[1,0]
	v_pk_mul_f32 v[16:17], v[16:17], v[0:1] op_sel_hi:[1,0]
	v_mfma_f32_32x32x16_bf16 v[32:47], v[172:175], v[48:51], v[32:47]
	v_sub_f32_e32 v10, v56, v119
	v_sub_f32_e32 v11, v57, v119
	v_sub_f32_e32 v12, v58, v119
	v_sub_f32_e32 v13, v59, v119
	v_sub_f32_e32 v14, v60, v119
	v_sub_f32_e32 v15, v61, v119
	v_sub_f32_e32 v52, v62, v119
	v_mfma_f32_32x32x16_bf16 v[16:31], v[180:183], v[48:51], v[16:31]
	v_sub_f32_e32 v49, v63, v119
	v_exp_f32_e32 v10, v10
	v_exp_f32_e32 v11, v11
	v_exp_f32_e32 v12, v12
	v_exp_f32_e32 v13, v13
	v_exp_f32_e32 v14, v14
	v_exp_f32_e32 v15, v15
	v_exp_f32_e32 v48, v52
	v_exp_f32_e32 v49, v49
	v_cvt_pk_bf16_f32 v50, v10, v11
	v_cvt_pk_bf16_f32 v51, v12, v13
	v_cvt_pk_bf16_f32 v52, v14, v15
	v_cvt_pk_bf16_f32 v53, v48, v49
	s_nop 1
	v_mfma_f32_32x32x16_bf16 v[32:47], v[176:179], v[50:53], v[32:47]
	v_mfma_f32_32x32x16_bf16 v[16:31], v[184:187], v[50:53], v[16:31]
	v_add_f32_e32 v2, 0, v2
	v_add_f32_e32 v2, v3, v2
	v_add_f32_e32 v2, v4, v2
	v_add_f32_e32 v2, v5, v2
	v_add_f32_e32 v2, v6, v2
	v_add_f32_e32 v2, v7, v2
	v_add_f32_e32 v2, v8, v2
	v_add_f32_e32 v2, v9, v2
	v_add_f32_e32 v2, v10, v2
	v_add_f32_e32 v2, v11, v2
	v_add_f32_e32 v2, v12, v2
	v_add_f32_e32 v2, v13, v2
	v_add_f32_e32 v2, v14, v2
	v_add_f32_e32 v2, v15, v2
	v_add_f32_e32 v2, v48, v2
	v_add_f32_e32 v189, v49, v2
	v_fmac_f32_e32 v189, v117, v0
	v_add3_u32 v50, s8, v148, v149
	s_waitcnt vmcnt(1)
	ds_write_b128 v50, v[96:99]
	s_and_saveexec_b64 s[2:3], s[0:1]
	v_add3_u32 v50, s8, v150, v156
	ds_write_b128 v50, v[64:67]
	s_or_b64 exec, exec, s[2:3]
	s_add_i32 s7, s7, 1
	v_mov_b32_e32 v96, v189
	v_add3_u32 v0, s8, v151, v152
	v_add_u32_e32 v113, 32, v113
	v_lshl_add_u64 v[126:127], v[126:127], 0, 64
	s_cmp_eq_u32 s7, 8
	v_add_u32_e32 v115, 32, v115
	s_waitcnt vmcnt(0)
	ds_write_b128 v0, v[92:95] offset:6656
	s_waitcnt lgkmcnt(0)
	s_barrier
	s_cbranch_scc0 .LBB0_389
	v_add3_u32 v0, s8, v153, v154
	ds_read_b128 v[122:125], v0
	ds_read_b128 v[126:129], v0 offset:32
	ds_read_b128 v[130:133], v0 offset:64
	ds_read_b128 v[134:137], v0 offset:96
	ds_read_b128 v[138:141], v0 offset:128
	ds_read_b128 v[160:163], v0 offset:160
	v_add3_u32 v0, s8, v102, v155
	v_add_u32_e32 v2, 0x1800, v0
	v_add_u32_e32 v0, 0x2000, v0
	v_mov_b32_e32 v14, v1
	v_mov_b32_e32 v15, v1
	ds_read2_b64 v[164:167], v2 offset0:64 offset1:66
	ds_read2_b64 v[64:67], v2 offset0:68 offset1:70
	ds_read2_b64 v[168:171], v0 offset0:128 offset1:130
	ds_read2_b64 v[92:95], v0 offset0:132 offset1:134
	v_mov_b32_e32 v0, v1
	v_mov_b32_e32 v2, v1
	v_mov_b32_e32 v3, v1
	v_mov_b32_e32 v4, v1
	v_mov_b32_e32 v5, v1
	v_mov_b32_e32 v6, v1
	v_mov_b32_e32 v7, v1
	v_mov_b32_e32 v8, v1
	v_mov_b32_e32 v9, v1
	v_mov_b32_e32 v10, v1
	v_mov_b32_e32 v11, v1
	v_mov_b32_e32 v12, v1
	v_mov_b32_e32 v13, v1
	v_mov_b64_e32 v[62:63], v[14:15]
	v_mov_b64_e32 v[60:61], v[12:13]
	v_mov_b64_e32 v[58:59], v[10:11]
	v_mov_b64_e32 v[56:57], v[8:9]
	v_mov_b64_e32 v[54:55], v[6:7]
	v_mov_b64_e32 v[52:53], v[4:5]
	v_mov_b64_e32 v[50:51], v[2:3]
	v_mov_b64_e32 v[48:49], v[0:1]
	s_ashr_i32 s7, s6, 31
	v_mov_b32_e32 v121, v1
	s_waitcnt lgkmcnt(9)
	v_mfma_f32_32x32x16_bf16 v[48:63], v[122:125], v[68:71], v[48:63]
	s_waitcnt lgkmcnt(0)
	s_barrier
	s_add_i32 s5, s5, s26
	v_mfma_f32_32x32x16_bf16 v[48:63], v[126:129], v[72:75], v[48:63]
	v_mfma_f32_32x32x16_bf16 v[48:63], v[130:133], v[76:79], v[48:63]
	v_mfma_f32_32x32x16_bf16 v[48:63], v[134:137], v[80:83], v[48:63]
	v_mfma_f32_32x32x16_bf16 v[48:63], v[138:141], v[84:87], v[48:63]
	v_mfma_f32_32x32x16_bf16 v[48:63], v[160:163], v[88:91], v[48:63]
	s_nop 11
	v_max_f32_e32 v0, v49, v49
	v_max_f32_e32 v2, v48, v48
	v_max_f32_e32 v0, v2, v0
	v_max3_f32 v0, v0, v50, v51
	v_max3_f32 v0, v0, v52, v53
	v_max3_f32 v0, v0, v54, v55
	v_max3_f32 v0, v0, v56, v57
	v_max3_f32 v0, v0, v58, v59
	v_max3_f32 v0, v0, v60, v61
	v_max3_f32 v0, v0, v62, v63
	ds_bpermute_b32 v2, v103, v0
	s_waitcnt lgkmcnt(0)
	v_max3_f32 v6, v119, v0, v2
	v_sub_f32_e32 v2, v48, v6
	v_sub_f32_e32 v3, v49, v6
	v_exp_f32_e32 v2, v2
	v_sub_f32_e32 v4, v50, v6
	v_exp_f32_e32 v3, v3
	v_sub_f32_e32 v5, v51, v6
	v_exp_f32_e32 v4, v4
	v_sub_f32_e32 v7, v52, v6
	v_exp_f32_e32 v5, v5
	v_sub_f32_e32 v8, v53, v6
	v_exp_f32_e32 v7, v7
	v_add_f32_e32 v49, 0, v2
	v_sub_f32_e32 v9, v54, v6
	v_exp_f32_e32 v8, v8
	v_add_f32_e32 v49, v3, v49
	v_sub_f32_e32 v10, v55, v6
	v_exp_f32_e32 v9, v9
	v_add_f32_e32 v49, v4, v49
	v_sub_f32_e32 v0, v119, v6
	v_sub_f32_e32 v11, v56, v6
	v_exp_f32_e32 v10, v10
	v_add_f32_e32 v49, v5, v49
	v_sub_f32_e32 v12, v57, v6
	v_exp_f32_e32 v11, v11
	v_add_f32_e32 v49, v7, v49
	v_exp_f32_e32 v0, v0
	v_sub_f32_e32 v13, v58, v6
	v_exp_f32_e32 v12, v12
	v_add_f32_e32 v49, v8, v49
	v_sub_f32_e32 v14, v59, v6
	v_exp_f32_e32 v13, v13
	v_add_f32_e32 v49, v9, v49
	v_sub_f32_e32 v15, v60, v6
	v_exp_f32_e32 v14, v14
	v_add_f32_e32 v49, v10, v49
	v_sub_f32_e32 v48, v61, v6
	v_exp_f32_e32 v15, v15
	v_add_f32_e32 v49, v11, v49
	v_pk_mul_f32 v[46:47], v[46:47], v[0:1] op_sel_hi:[1,0]
	v_pk_mul_f32 v[44:45], v[44:45], v[0:1] op_sel_hi:[1,0]
	v_pk_mul_f32 v[42:43], v[42:43], v[0:1] op_sel_hi:[1,0]
	v_pk_mul_f32 v[40:41], v[40:41], v[0:1] op_sel_hi:[1,0]
	v_pk_mul_f32 v[38:39], v[38:39], v[0:1] op_sel_hi:[1,0]
	v_pk_mul_f32 v[36:37], v[36:37], v[0:1] op_sel_hi:[1,0]
	v_pk_mul_f32 v[34:35], v[34:35], v[0:1] op_sel_hi:[1,0]
	v_pk_mul_f32 v[32:33], v[32:33], v[0:1] op_sel_hi:[1,0]
	v_pk_mul_f32 v[30:31], v[30:31], v[0:1] op_sel_hi:[1,0]
	v_cvt_pk_bf16_f32 v2, v2, v3
	v_cvt_pk_bf16_f32 v3, v4, v5
	v_cvt_pk_bf16_f32 v4, v7, v8
	v_cvt_pk_bf16_f32 v5, v9, v10
	v_pk_mul_f32 v[28:29], v[28:29], v[0:1] op_sel_hi:[1,0]
	v_pk_mul_f32 v[26:27], v[26:27], v[0:1] op_sel_hi:[1,0]
	v_pk_mul_f32 v[24:25], v[24:25], v[0:1] op_sel_hi:[1,0]
	v_pk_mul_f32 v[22:23], v[22:23], v[0:1] op_sel_hi:[1,0]
	v_pk_mul_f32 v[20:21], v[20:21], v[0:1] op_sel_hi:[1,0]
	v_pk_mul_f32 v[18:19], v[18:19], v[0:1] op_sel_hi:[1,0]
	v_pk_mul_f32 v[16:17], v[16:17], v[0:1] op_sel_hi:[1,0]
	v_exp_f32_e32 v48, v48
	v_add_f32_e32 v49, v12, v49
	v_sub_f32_e32 v50, v62, v6
	v_mfma_f32_32x32x16_bf16 v[32:47], v[164:167], v[2:5], v[32:47]
	v_add_f32_e32 v49, v13, v49
	v_exp_f32_e32 v7, v50
	v_add_f32_e32 v49, v14, v49
	v_add_f32_e32 v49, v15, v49
	v_add_f32_e32 v49, v48, v49
	v_mfma_f32_32x32x16_bf16 v[16:31], v[168:171], v[2:5], v[16:31]
	v_sub_f32_e32 v2, v63, v6
	v_exp_f32_e32 v6, v2
	v_cvt_pk_bf16_f32 v2, v11, v12
	v_cvt_pk_bf16_f32 v3, v13, v14
	v_cvt_pk_bf16_f32 v4, v15, v48
	v_cvt_pk_bf16_f32 v5, v7, v6
	v_add_f32_e32 v7, v7, v49
	v_add_f32_e32 v6, v6, v7
	v_fmac_f32_e32 v6, v96, v0
	ds_bpermute_b32 v0, v103, v6
	v_mfma_f32_32x32x16_bf16 v[32:47], v[64:67], v[2:5], v[32:47]
	s_waitcnt lgkmcnt(0)
	v_add_f32_e32 v0, v6, v0
	v_mfma_f32_32x32x16_bf16 v[16:31], v[92:95], v[2:5], v[16:31]
	v_div_scale_f32 v2, s[2:3], v0, v0, 1.0
	v_rcp_f32_e32 v3, v2
	v_readlane_b32 s2, v253, 6
	v_readlane_b32 s3, v253, 7
	v_fma_f32 v4, -v2, v3, 1.0
	v_fmac_f32_e32 v3, v4, v3
	v_div_scale_f32 v4, vcc, 1.0, v0, 1.0
	v_mul_f32_e32 v5, v4, v3
	v_fma_f32 v6, -v2, v5, v4
	v_fmac_f32_e32 v5, v6, v3
	v_fma_f32 v2, -v2, v5, v4
	v_div_fmas_f32 v2, v2, v3, v5
	v_div_fixup_f32 v0, v2, v0, 1.0
	v_lshl_add_u64 v[2:3], s[6:7], 0, v[108:109]
	v_lshlrev_b64 v[2:3], 10, v[2:3]
	v_lshl_add_u64 v[2:3], s[2:3], 0, v[2:3]
	s_lshl_b32 s2, s12, 1
	s_mov_b32 s3, s4
	v_lshl_add_u64 v[2:3], v[2:3], 0, s[2:3]
	v_pk_mul_f32 v[4:5], v[32:33], v[0:1] op_sel_hi:[1,0]
	v_pk_mul_f32 v[6:7], v[34:35], v[0:1] op_sel_hi:[1,0]
	v_lshl_add_u64 v[2:3], v[2:3], 0, v[120:121]
	v_cvt_pk_bf16_f32 v4, v4, v5
	v_cvt_pk_bf16_f32 v5, v6, v7
	global_store_dwordx2 v[2:3], v[4:5], off
	v_pk_mul_f32 v[4:5], v[16:17], v[0:1] op_sel_hi:[1,0]
	v_pk_mul_f32 v[6:7], v[18:19], v[0:1] op_sel_hi:[1,0]
	v_cvt_pk_bf16_f32 v4, v4, v5
	v_cvt_pk_bf16_f32 v5, v6, v7
	global_store_dwordx2 v[2:3], v[4:5], off offset:64
	v_pk_mul_f32 v[4:5], v[36:37], v[0:1] op_sel_hi:[1,0]
	v_pk_mul_f32 v[6:7], v[38:39], v[0:1] op_sel_hi:[1,0]
	v_cvt_pk_bf16_f32 v4, v4, v5
	v_cvt_pk_bf16_f32 v5, v6, v7
	global_store_dwordx2 v[2:3], v[4:5], off offset:16
	v_pk_mul_f32 v[4:5], v[20:21], v[0:1] op_sel_hi:[1,0]
	v_pk_mul_f32 v[6:7], v[22:23], v[0:1] op_sel_hi:[1,0]
	v_cvt_pk_bf16_f32 v4, v4, v5
	v_cvt_pk_bf16_f32 v5, v6, v7
	global_store_dwordx2 v[2:3], v[4:5], off offset:80
	v_pk_mul_f32 v[4:5], v[40:41], v[0:1] op_sel_hi:[1,0]
	v_pk_mul_f32 v[6:7], v[42:43], v[0:1] op_sel_hi:[1,0]
	v_cvt_pk_bf16_f32 v4, v4, v5
	v_cvt_pk_bf16_f32 v5, v6, v7
	global_store_dwordx2 v[2:3], v[4:5], off offset:32
	v_pk_mul_f32 v[4:5], v[24:25], v[0:1] op_sel_hi:[1,0]
	v_pk_mul_f32 v[6:7], v[26:27], v[0:1] op_sel_hi:[1,0]
	v_cvt_pk_bf16_f32 v4, v4, v5
	v_cvt_pk_bf16_f32 v5, v6, v7
	global_store_dwordx2 v[2:3], v[4:5], off offset:96
	v_pk_mul_f32 v[4:5], v[44:45], v[0:1] op_sel_hi:[1,0]
	v_pk_mul_f32 v[6:7], v[46:47], v[0:1] op_sel_hi:[1,0]
	v_cvt_pk_bf16_f32 v4, v4, v5
	v_cvt_pk_bf16_f32 v5, v6, v7
	global_store_dwordx2 v[2:3], v[4:5], off offset:48
	v_pk_mul_f32 v[4:5], v[28:29], v[0:1] op_sel_hi:[1,0]
	v_pk_mul_f32 v[6:7], v[30:31], v[0:1] op_sel_hi:[1,0]
	v_cvt_pk_bf16_f32 v4, v4, v5
	v_cvt_pk_bf16_f32 v5, v6, v7
	s_cmpk_gt_i32 s5, 0xff
	global_store_dwordx2 v[2:3], v[4:5], off offset:112
	s_cbranch_scc0 .LBB0_384
